# final RMSNorm loop hand-written: gain loaded once, row loads one row ahead, DPP row sum, no drains between stores
# speedup vs baseline: 1.0138x; 1.0003x over previous
; DI float bflo(unsigned w) { return __uint_as_float(w << 16); }
; DI float bfhi(unsigned w) { return __uint_as_float(w & 0xffff0000u); }
; #define INP(i) ((const float*)karg(8 * (i)))
; __global__ void __launch_bounds__(NWAVES * 64, 2) fwd_megakernel(Args A) {
;     ...
;     {
;         LAUNDER_TID
;         const float* gn = INP(19);
;         const int gw = vcu * NWAVES + wave, NGW = G * NWAVES;
;         for (int m = xl ? xq * 4096 + rk * NWAVES + wave : gw; m < (xl ? (xq + 1) * 4096 : M); m += (xl ? nl * NWAVES : NGW)) {
;             float s = lane < 16 ? SSQ[(size_t)m * 16 + lane] : 0.f; s = wave_sum(s);
;             const float rstd = rsqrtf(s * (1.0f / DM) + EPS);
;             f32x4* xr = (f32x4*)(X + (size_t)m * DM) + lane; const f32x4* gr = (const f32x4*)gn + lane; const u32x2* xb = (const u32x2*)(XB + (size_t)m * DM) + lane;
; #pragma unroll
;             for (int j = 0; j < 4; ++j) { const u32x2 bb = xb[64 * j]; const f32x4 v = {bflo(bb.x), bfhi(bb.x), bflo(bb.y), bfhi(bb.y)}; xr[64 * j] = v * rstd * gr[64 * j]; }
.LBB0_1315:
	v_readlane_b32 s4, v245, 17
	s_lshl_b32 s8, s4, 12
	v_readfirstlane_b32 s2, v165
	s_and_b32 s4, s17, -8
	s_ashr_i32 s3, s2, 6
	s_add_i32 s9, s8, s4
	s_lshl_b32 s10, s17, 3
	s_and_b64 s[4:5], s[6:7], exec
	s_cselect_b32 s4, s9, s10
	s_add_i32 s10, s3, s4
	s_add_i32 s5, s8, 0x1000
	s_and_b64 s[8:9], s[6:7], exec
	s_cselect_b32 s11, s5, 0x8000
	s_movk_i32 s2, 0x98
	s_cmp_ge_i32 s10, s11
	s_cbranch_scc1 .LBB0_1320
	s_ashr_i32 s5, s2, 31
	s_add_u32 s0, s0, s2
	v_and_b32_e32 v0, 64, v194
	s_addc_u32 s1, s1, s5
	v_add_u32_e32 v0, 64, v0
	v_xor_b32_e32 v1, 1, v194
	s_load_dwordx2 s[8:9], s[0:1], 0x0
	v_cmp_lt_i32_e64 s[0:1], v1, v0
	s_and_b32 s2, s80, -8
	v_and_b32_e32 v4, 63, v165
	v_cndmask_b32_e64 v1, v194, v1, s[0:1]
	v_lshlrev_b32_e32 v8, 2, v1
	v_xor_b32_e32 v1, 2, v194
	v_cmp_lt_i32_e64 s[0:1], v1, v0
	v_mov_b32_e32 v7, 0
	v_lshlrev_b32_e32 v2, 2, v4
	v_cndmask_b32_e64 v1, v194, v1, s[0:1]
	v_lshlrev_b32_e32 v9, 2, v1
	v_xor_b32_e32 v1, 4, v194
	v_cmp_lt_i32_e64 s[0:1], v1, v0
	v_mov_b32_e32 v3, v7
	v_cmp_gt_u32_e32 vcc, 16, v4
	v_cndmask_b32_e64 v1, v194, v1, s[0:1]
	v_lshlrev_b32_e32 v10, 2, v1
	v_xor_b32_e32 v1, 8, v194
	v_cmp_lt_i32_e64 s[0:1], v1, v0
	v_lshlrev_b32_e32 v6, 4, v4
	v_lshlrev_b32_e32 v4, 3, v4
	v_cndmask_b32_e64 v1, v194, v1, s[0:1]
	v_lshlrev_b32_e32 v11, 2, v1
	v_xor_b32_e32 v1, 16, v194
	v_cmp_lt_i32_e64 s[0:1], v1, v0
	v_mov_b32_e32 v5, v7
	v_mov_b32_e32 v14, 0x358637bd
	v_cndmask_b32_e64 v1, v194, v1, s[0:1]
	v_lshlrev_b32_e32 v12, 2, v1
	v_xor_b32_e32 v1, 32, v194
	v_cmp_lt_i32_e64 s[0:1], v1, v0
	s_nop 1
	v_cndmask_b32_e64 v0, v194, v1, s[0:1]
	s_and_b64 s[0:1], s[6:7], exec
	v_readlane_b32 s0, v246, 2
	v_readlane_b32 s1, v246, 3
	s_cselect_b32 s2, s2, s0
	s_ashr_i32 s1, s4, 31
	s_ashr_i32 s5, s3, 31
	s_add_u32 s0, s4, s3
	s_addc_u32 s1, s1, s5
	s_lshl_b64 s[4:5], s[0:1], 6
	s_add_u32 s4, s76, s4
	s_addc_u32 s5, s77, s5
	v_lshl_add_u64 v[2:3], s[4:5], 0, v[2:3]
	s_mov_b64 s[4:5], 0x9400000
	s_ashr_i32 s3, s2, 31
	v_lshl_add_u64 v[2:3], v[2:3], 0, s[4:5]
	s_lshl_b64 s[4:5], s[2:3], 6
	s_lshl_b64 s[6:7], s[0:1], 11
	s_add_u32 s6, s76, s6
	s_addc_u32 s7, s77, s7
	v_lshl_add_u64 v[4:5], s[6:7], 0, v[4:5]
	s_mov_b64 s[6:7], 0x5400400
	v_lshlrev_b32_e32 v13, 2, v0
	s_waitcnt lgkmcnt(0)
	v_lshl_add_u64 v[0:1], s[8:9], 0, v[6:7]
	v_lshl_add_u64 v[4:5], v[4:5], 0, s[6:7]
	s_lshl_b64 s[6:7], s[2:3], 11
	s_lshl_b64 s[0:1], s[0:1], 12
	v_readlane_b32 s8, v246, 0
	v_readlane_b32 s9, v246, 1
	s_add_u32 s0, s8, s0
	s_addc_u32 s1, s9, s1
	v_lshl_add_u64 v[6:7], s[0:1], 0, v[6:7]
	s_mov_b64 s[0:1], 0xc00
	v_lshl_add_u64 v[6:7], v[6:7], 0, s[0:1]
	s_lshl_b64 s[8:9], s[2:3], 12
	s_mov_b32 s3, 0x800000
	global_load_dwordx4 v[40:43], v[0:1], off
	global_load_dwordx4 v[44:47], v[0:1], off offset:1024
	global_load_dwordx4 v[48:51], v[0:1], off offset:2048
	global_load_dwordx4 v[52:55], v[0:1], off offset:3072
	v_mov_b32_e32 v15, 0
	s_and_saveexec_b64 s[0:1], vcc
	global_load_dword v15, v[2:3], off
	s_or_b64 exec, exec, s[0:1]
	global_load_dwordx2 v[16:17], v[4:5], off offset:-1024
	global_load_dwordx2 v[18:19], v[4:5], off offset:-512
	global_load_dwordx2 v[20:21], v[4:5], off
	global_load_dwordx2 v[22:23], v[4:5], off offset:512
; DI float bflo(unsigned w) { return __uint_as_float(w << 16); }
; DI float bfhi(unsigned w) { return __uint_as_float(w & 0xffff0000u); }
; __global__ void __launch_bounds__(NWAVES * 64, 2) fwd_megakernel(Args A) {
;     ...
;         for (int m = xl ? xq * 4096 + rk * NWAVES + wave : gw; m < (xl ? (xq + 1) * 4096 : M); m += (xl ? nl * NWAVES : NGW)) {
;             float s = lane < 16 ? SSQ[(size_t)m * 16 + lane] : 0.f; s = wave_sum(s);
;             const float rstd = rsqrtf(s * (1.0f / DM) + EPS);
;             f32x4* xr = (f32x4*)(X + (size_t)m * DM) + lane; const f32x4* gr = (const f32x4*)gn + lane; const u32x2* xb = (const u32x2*)(XB + (size_t)m * DM) + lane;
; #pragma unroll
;             for (int j = 0; j < 4; ++j) { const u32x2 bb = xb[64 * j]; const f32x4 v = {bflo(bb.x), bfhi(bb.x), bflo(bb.y), bfhi(bb.y)}; xr[64 * j] = v * rstd * gr[64 * j]; }
.Lfn_A:
	s_add_i32 s10, s10, s2
	s_cmp_lt_i32 s10, s11
	s_cselect_b32 s12, s4, 0
	s_cselect_b32 s13, s5, 0
	s_cselect_b32 s14, s6, 0
	s_cselect_b32 s15, s7, 0
	s_cselect_b64 s[16:17], -1, 0
	v_lshl_add_u64 v[2:3], v[2:3], 0, s[12:13]
	v_lshl_add_u64 v[4:5], v[4:5], 0, s[14:15]
	v_mov_b32_e32 v24, 0
	s_and_saveexec_b64 s[0:1], vcc
	global_load_dword v24, v[2:3], off
	s_or_b64 exec, exec, s[0:1]
	global_load_dwordx2 v[26:27], v[4:5], off offset:-1024
	global_load_dwordx2 v[28:29], v[4:5], off offset:-512
	global_load_dwordx2 v[30:31], v[4:5], off
	global_load_dwordx2 v[32:33], v[4:5], off offset:512
	s_waitcnt vmcnt(5)
	s_nop 1
	v_add_f32_dpp v15, v15, v15 quad_perm:[1,0,3,2] row_mask:0xf bank_mask:0xf
	s_nop 1
	v_add_f32_dpp v15, v15, v15 quad_perm:[2,3,0,1] row_mask:0xf bank_mask:0xf
	s_nop 1
	v_add_f32_dpp v15, v15, v15 row_half_mirror row_mask:0xf bank_mask:0xf
	s_nop 1
	v_add_f32_dpp v15, v15, v15 row_mirror row_mask:0xf bank_mask:0xf
	s_nop 1
	v_readfirstlane_b32 s18, v15
	v_mov_b32_e32 v34, s18
	v_fmamk_f32 v34, v34, 0x3a800000, v14
	v_mul_f32_e32 v35, 0x4b800000, v34
	v_cmp_gt_f32_e64 s[0:1], s3, v34
	v_cndmask_b32_e64 v34, v34, v35, s[0:1]
	v_rsq_f32_e32 v34, v34
	s_nop 0
	v_mul_f32_e32 v35, 0x45800000, v34
	v_cndmask_b32_e64 v34, v34, v35, s[0:1]
	v_lshlrev_b32_e32 v36, 16, v16
	v_and_b32_e32 v37, 0xffff0000, v16
	v_lshlrev_b32_e32 v38, 16, v17
	v_and_b32_e32 v39, 0xffff0000, v17
	v_pk_mul_f32 v[36:37], v[34:35], v[36:37] op_sel_hi:[0,1]
	v_pk_mul_f32 v[38:39], v[34:35], v[38:39] op_sel_hi:[0,1]
	v_pk_mul_f32 v[36:37], v[40:41], v[36:37]
	v_pk_mul_f32 v[38:39], v[42:43], v[38:39]
	global_store_dwordx4 v[6:7], v[36:39], off offset:-3072
	v_lshlrev_b32_e32 v56, 16, v18
	v_and_b32_e32 v57, 0xffff0000, v18
	v_lshlrev_b32_e32 v58, 16, v19
	v_and_b32_e32 v59, 0xffff0000, v19
	v_pk_mul_f32 v[56:57], v[34:35], v[56:57] op_sel_hi:[0,1]
	v_pk_mul_f32 v[58:59], v[34:35], v[58:59] op_sel_hi:[0,1]
	v_pk_mul_f32 v[56:57], v[44:45], v[56:57]
	v_pk_mul_f32 v[58:59], v[46:47], v[58:59]
	global_store_dwordx4 v[6:7], v[56:59], off offset:-2048
	v_lshlrev_b32_e32 v60, 16, v20
	v_and_b32_e32 v61, 0xffff0000, v20
	v_lshlrev_b32_e32 v62, 16, v21
	v_and_b32_e32 v63, 0xffff0000, v21
	v_pk_mul_f32 v[60:61], v[34:35], v[60:61] op_sel_hi:[0,1]
	v_pk_mul_f32 v[62:63], v[34:35], v[62:63] op_sel_hi:[0,1]
	v_pk_mul_f32 v[60:61], v[48:49], v[60:61]
	v_pk_mul_f32 v[62:63], v[50:51], v[62:63]
	global_store_dwordx4 v[6:7], v[60:63], off offset:-1024
	v_lshlrev_b32_e32 v64, 16, v22
	v_and_b32_e32 v65, 0xffff0000, v22
	v_lshlrev_b32_e32 v66, 16, v23
	v_and_b32_e32 v67, 0xffff0000, v23
	v_pk_mul_f32 v[64:65], v[34:35], v[64:65] op_sel_hi:[0,1]
	v_pk_mul_f32 v[66:67], v[34:35], v[66:67] op_sel_hi:[0,1]
	v_pk_mul_f32 v[64:65], v[52:53], v[64:65]
	v_pk_mul_f32 v[66:67], v[54:55], v[66:67]
	global_store_dwordx4 v[6:7], v[64:67], off
	v_lshl_add_u64 v[6:7], v[6:7], 0, s[8:9]
	s_and_b64 s[18:19], s[16:17], exec
	s_cbranch_scc0 .LBB0_1320
	s_add_i32 s10, s10, s2
	s_cmp_lt_i32 s10, s11
	s_cselect_b32 s12, s4, 0
	s_cselect_b32 s13, s5, 0
	s_cselect_b32 s14, s6, 0
	s_cselect_b32 s15, s7, 0
	s_cselect_b64 s[16:17], -1, 0
	v_lshl_add_u64 v[2:3], v[2:3], 0, s[12:13]
	v_lshl_add_u64 v[4:5], v[4:5], 0, s[14:15]
	v_mov_b32_e32 v15, 0
	s_and_saveexec_b64 s[0:1], vcc
	global_load_dword v15, v[2:3], off
	s_or_b64 exec, exec, s[0:1]
	global_load_dwordx2 v[16:17], v[4:5], off offset:-1024
	global_load_dwordx2 v[18:19], v[4:5], off offset:-512
	global_load_dwordx2 v[20:21], v[4:5], off
	global_load_dwordx2 v[22:23], v[4:5], off offset:512
	s_waitcnt vmcnt(5)
	s_nop 1
	v_add_f32_dpp v24, v24, v24 quad_perm:[1,0,3,2] row_mask:0xf bank_mask:0xf
	s_nop 1
	v_add_f32_dpp v24, v24, v24 quad_perm:[2,3,0,1] row_mask:0xf bank_mask:0xf
	s_nop 1
	v_add_f32_dpp v24, v24, v24 row_half_mirror row_mask:0xf bank_mask:0xf
	s_nop 1
	v_add_f32_dpp v24, v24, v24 row_mirror row_mask:0xf bank_mask:0xf
	s_nop 1
	v_readfirstlane_b32 s18, v24
	v_mov_b32_e32 v34, s18
	v_fmamk_f32 v34, v34, 0x3a800000, v14
	v_mul_f32_e32 v35, 0x4b800000, v34
	v_cmp_gt_f32_e64 s[0:1], s3, v34
	v_cndmask_b32_e64 v34, v34, v35, s[0:1]
	v_rsq_f32_e32 v34, v34
	s_nop 0
	v_mul_f32_e32 v35, 0x45800000, v34
	v_cndmask_b32_e64 v34, v34, v35, s[0:1]
	v_lshlrev_b32_e32 v36, 16, v26
	v_and_b32_e32 v37, 0xffff0000, v26
	v_lshlrev_b32_e32 v38, 16, v27
	v_and_b32_e32 v39, 0xffff0000, v27
	v_pk_mul_f32 v[36:37], v[34:35], v[36:37] op_sel_hi:[0,1]
	v_pk_mul_f32 v[38:39], v[34:35], v[38:39] op_sel_hi:[0,1]
	v_pk_mul_f32 v[36:37], v[40:41], v[36:37]
	v_pk_mul_f32 v[38:39], v[42:43], v[38:39]
	global_store_dwordx4 v[6:7], v[36:39], off offset:-3072
	v_lshlrev_b32_e32 v56, 16, v28
	v_and_b32_e32 v57, 0xffff0000, v28
	v_lshlrev_b32_e32 v58, 16, v29
	v_and_b32_e32 v59, 0xffff0000, v29
	v_pk_mul_f32 v[56:57], v[34:35], v[56:57] op_sel_hi:[0,1]
	v_pk_mul_f32 v[58:59], v[34:35], v[58:59] op_sel_hi:[0,1]
	v_pk_mul_f32 v[56:57], v[44:45], v[56:57]
	v_pk_mul_f32 v[58:59], v[46:47], v[58:59]
	global_store_dwordx4 v[6:7], v[56:59], off offset:-2048
	v_lshlrev_b32_e32 v60, 16, v30
	v_and_b32_e32 v61, 0xffff0000, v30
	v_lshlrev_b32_e32 v62, 16, v31
	v_and_b32_e32 v63, 0xffff0000, v31
	v_pk_mul_f32 v[60:61], v[34:35], v[60:61] op_sel_hi:[0,1]
	v_pk_mul_f32 v[62:63], v[34:35], v[62:63] op_sel_hi:[0,1]
	v_pk_mul_f32 v[60:61], v[48:49], v[60:61]
	v_pk_mul_f32 v[62:63], v[50:51], v[62:63]
	global_store_dwordx4 v[6:7], v[60:63], off offset:-1024
	v_lshlrev_b32_e32 v64, 16, v32
	v_and_b32_e32 v65, 0xffff0000, v32
	v_lshlrev_b32_e32 v66, 16, v33
	v_and_b32_e32 v67, 0xffff0000, v33
	v_pk_mul_f32 v[64:65], v[34:35], v[64:65] op_sel_hi:[0,1]
	v_pk_mul_f32 v[66:67], v[34:35], v[66:67] op_sel_hi:[0,1]
	v_pk_mul_f32 v[64:65], v[52:53], v[64:65]
	v_pk_mul_f32 v[66:67], v[54:55], v[66:67]
	global_store_dwordx4 v[6:7], v[64:67], off
	v_lshl_add_u64 v[6:7], v[6:7], 0, s[8:9]
	s_and_b64 s[18:19], s[16:17], exec
	s_cbranch_scc1 .Lfn_A
